# FFN GEMM loops: DMA source addresses formed on SALU (saddr-form global_load_lds), no 64-bit VALU adds in the loading wave; plus setprio/waitcnt cleanup
# speedup vs baseline: 1.0094x; 1.0094x over previous
.LBB0_182:
	ds_read_b128 v[144:147], v153 offset:0
	ds_read_b128 v[156:159], v153 offset:1024
	ds_read_b128 v[160:163], v153 offset:2048
	ds_read_b128 v[164:167], v153 offset:3072
	ds_read_b128 v[168:171], v154 offset:0
	ds_read_b128 v[172:175], v154 offset:1024
	ds_read_b128 v[176:179], v154 offset:2048
	ds_read_b128 v[180:183], v154 offset:3072
	s_add_u32 s30, s72, 0xfff00080
	s_addc_u32 s31, s73, -1
	s_cmp_eq_u32 s41, 60
	s_cselect_b32 s31, s13, s31
	s_cselect_b32 s30, s37, s30
	s_cselect_b32 s75, s11, s40
	s_cselect_b32 s74, s38, s39
	ds_read_b128 v[184:187], v155 offset:0
	ds_read_b128 v[188:191], v155 offset:1024
	ds_read_b128 v[192:195], v155 offset:2048
	ds_read_b128 v[196:199], v155 offset:3072
	ds_read_b128 v[200:203], v155 offset:4096
	ds_read_b128 v[204:207], v155 offset:5120
	ds_read_b128 v[208:211], v155 offset:6144
	ds_read_b128 v[212:215], v155 offset:7168
	s_add_i32 m0, s29, 0xc000
	s_nop 0
	global_load_lds_dwordx4 v136, s[72:73]
	s_add_i32 m0, s29, 0xe000
	s_nop 0
	global_load_lds_dwordx4 v138, s[72:73]
	s_waitcnt vmcnt(8)
	s_waitcnt lgkmcnt(0)
	s_barrier
	s_setprio 1
	v_mfma_f32_16x16x32_bf16 v[124:127], v[144:147], v[184:187], v[124:127]
	v_mfma_f32_16x16x32_bf16 v[120:123], v[160:163], v[184:187], v[120:123]
	v_mfma_f32_16x16x32_bf16 v[108:111], v[144:147], v[192:195], v[108:111]
	v_mfma_f32_16x16x32_bf16 v[104:107], v[160:163], v[192:195], v[104:107]
	v_mfma_f32_16x16x32_bf16 v[92:95], v[144:147], v[200:203], v[92:95]
	v_mfma_f32_16x16x32_bf16 v[88:91], v[160:163], v[200:203], v[88:91]
	v_mfma_f32_16x16x32_bf16 v[76:79], v[144:147], v[208:211], v[76:79]
	v_mfma_f32_16x16x32_bf16 v[72:75], v[160:163], v[208:211], v[72:75]
	v_mfma_f32_16x16x32_bf16 v[124:127], v[156:159], v[188:191], v[124:127]
	v_mfma_f32_16x16x32_bf16 v[120:123], v[164:167], v[188:191], v[120:123]
	v_mfma_f32_16x16x32_bf16 v[108:111], v[156:159], v[196:199], v[108:111]
	v_mfma_f32_16x16x32_bf16 v[104:107], v[164:167], v[196:199], v[104:107]
	v_mfma_f32_16x16x32_bf16 v[92:95], v[156:159], v[204:207], v[92:95]
	v_mfma_f32_16x16x32_bf16 v[88:91], v[164:167], v[204:207], v[88:91]
	v_mfma_f32_16x16x32_bf16 v[76:79], v[156:159], v[212:215], v[76:79]
	v_mfma_f32_16x16x32_bf16 v[72:75], v[164:167], v[212:215], v[72:75]
	v_mfma_f32_16x16x32_bf16 v[116:119], v[168:171], v[184:187], v[116:119]
	v_mfma_f32_16x16x32_bf16 v[112:115], v[176:179], v[184:187], v[112:115]
	v_mfma_f32_16x16x32_bf16 v[100:103], v[168:171], v[192:195], v[100:103]
	v_mfma_f32_16x16x32_bf16 v[96:99], v[176:179], v[192:195], v[96:99]
	v_mfma_f32_16x16x32_bf16 v[84:87], v[168:171], v[200:203], v[84:87]
	v_mfma_f32_16x16x32_bf16 v[80:83], v[176:179], v[200:203], v[80:83]
	v_mfma_f32_16x16x32_bf16 v[68:71], v[168:171], v[208:211], v[68:71]
	v_mfma_f32_16x16x32_bf16 v[64:67], v[176:179], v[208:211], v[64:67]
	v_mfma_f32_16x16x32_bf16 v[116:119], v[172:175], v[188:191], v[116:119]
	v_mfma_f32_16x16x32_bf16 v[112:115], v[180:183], v[188:191], v[112:115]
	v_mfma_f32_16x16x32_bf16 v[100:103], v[172:175], v[196:199], v[100:103]
	v_mfma_f32_16x16x32_bf16 v[96:99], v[180:183], v[196:199], v[96:99]
	v_mfma_f32_16x16x32_bf16 v[84:87], v[172:175], v[204:207], v[84:87]
	v_mfma_f32_16x16x32_bf16 v[80:83], v[180:183], v[204:207], v[80:83]
	v_mfma_f32_16x16x32_bf16 v[68:71], v[172:175], v[212:215], v[68:71]
	v_mfma_f32_16x16x32_bf16 v[64:67], v[180:183], v[212:215], v[64:67]
	s_setprio 0
	s_barrier
	s_add_u32 s42, s74, 0x100000
	s_addc_u32 s43, s75, 0
	ds_read_b128 v[184:187], v155 offset:16384
	ds_read_b128 v[188:191], v155 offset:17408
	ds_read_b128 v[192:195], v155 offset:18432
	ds_read_b128 v[196:199], v155 offset:19456
	ds_read_b128 v[200:203], v155 offset:20480
	ds_read_b128 v[204:207], v155 offset:21504
	ds_read_b128 v[208:211], v155 offset:22528
	ds_read_b128 v[212:215], v155 offset:23552
	s_add_i32 m0, s29, 0x10000
	s_nop 0
	global_load_lds_dwordx4 v130, s[74:75]
	s_add_i32 m0, s29, 0x12000
	s_nop 0
	global_load_lds_dwordx4 v134, s[74:75]
	s_add_i32 m0, s29, 0x14000
	s_nop 0
	global_load_lds_dwordx4 v130, s[42:43]
	s_add_i32 m0, s29, 0x16000
	s_nop 0
	global_load_lds_dwordx4 v134, s[42:43]
	s_add_i32 m0, s29, 0x0
	s_nop 0
	global_load_lds_dwordx4 v128, s[30:31]
	s_add_i32 m0, s29, 0x2000
	s_nop 0
	global_load_lds_dwordx4 v132, s[30:31]
	s_waitcnt vmcnt(8)
	s_waitcnt lgkmcnt(0)
	s_barrier
	s_setprio 1
	v_mfma_f32_16x16x32_bf16 v[60:63], v[144:147], v[184:187], v[60:63]
	v_mfma_f32_16x16x32_bf16 v[56:59], v[160:163], v[184:187], v[56:59]
	v_mfma_f32_16x16x32_bf16 v[44:47], v[144:147], v[192:195], v[44:47]
	v_mfma_f32_16x16x32_bf16 v[40:43], v[160:163], v[192:195], v[40:43]
	v_mfma_f32_16x16x32_bf16 v[28:31], v[144:147], v[200:203], v[28:31]
	v_mfma_f32_16x16x32_bf16 v[24:27], v[160:163], v[200:203], v[24:27]
	v_mfma_f32_16x16x32_bf16 v[12:15], v[144:147], v[208:211], v[12:15]
	v_mfma_f32_16x16x32_bf16 v[8:11], v[160:163], v[208:211], v[8:11]
	v_mfma_f32_16x16x32_bf16 v[60:63], v[156:159], v[188:191], v[60:63]
	v_mfma_f32_16x16x32_bf16 v[56:59], v[164:167], v[188:191], v[56:59]
	v_mfma_f32_16x16x32_bf16 v[44:47], v[156:159], v[196:199], v[44:47]
	v_mfma_f32_16x16x32_bf16 v[40:43], v[164:167], v[196:199], v[40:43]
	v_mfma_f32_16x16x32_bf16 v[28:31], v[156:159], v[204:207], v[28:31]
	v_mfma_f32_16x16x32_bf16 v[24:27], v[164:167], v[204:207], v[24:27]
	v_mfma_f32_16x16x32_bf16 v[12:15], v[156:159], v[212:215], v[12:15]
	v_mfma_f32_16x16x32_bf16 v[8:11], v[164:167], v[212:215], v[8:11]
	v_mfma_f32_16x16x32_bf16 v[52:55], v[168:171], v[184:187], v[52:55]
	v_mfma_f32_16x16x32_bf16 v[48:51], v[176:179], v[184:187], v[48:51]
	v_mfma_f32_16x16x32_bf16 v[36:39], v[168:171], v[192:195], v[36:39]
	v_mfma_f32_16x16x32_bf16 v[32:35], v[176:179], v[192:195], v[32:35]
	v_mfma_f32_16x16x32_bf16 v[20:23], v[168:171], v[200:203], v[20:23]
	v_mfma_f32_16x16x32_bf16 v[16:19], v[176:179], v[200:203], v[16:19]
	v_mfma_f32_16x16x32_bf16 v[4:7], v[168:171], v[208:211], v[4:7]
	v_mfma_f32_16x16x32_bf16 v[0:3], v[176:179], v[208:211], v[0:3]
	v_mfma_f32_16x16x32_bf16 v[52:55], v[172:175], v[188:191], v[52:55]
	v_mfma_f32_16x16x32_bf16 v[48:51], v[180:183], v[188:191], v[48:51]
	v_mfma_f32_16x16x32_bf16 v[36:39], v[172:175], v[196:199], v[36:39]
	v_mfma_f32_16x16x32_bf16 v[32:35], v[180:183], v[196:199], v[32:35]
	v_mfma_f32_16x16x32_bf16 v[20:23], v[172:175], v[204:207], v[20:23]
	v_mfma_f32_16x16x32_bf16 v[16:19], v[180:183], v[204:207], v[16:19]
	v_mfma_f32_16x16x32_bf16 v[4:7], v[172:175], v[212:215], v[4:7]
	v_mfma_f32_16x16x32_bf16 v[0:3], v[180:183], v[212:215], v[0:3]
	s_setprio 0
	s_barrier
	s_add_u32 s98, s30, 0x100000
	s_addc_u32 s99, s31, 0
	ds_read_b128 v[144:147], v153 offset:32768
	ds_read_b128 v[156:159], v153 offset:33792
	ds_read_b128 v[160:163], v153 offset:34816
	ds_read_b128 v[164:167], v153 offset:35840
	ds_read_b128 v[168:171], v154 offset:32768
	ds_read_b128 v[172:175], v154 offset:33792
	ds_read_b128 v[176:179], v154 offset:34816
	ds_read_b128 v[180:183], v154 offset:35840
	ds_read_b128 v[184:187], v155 offset:32768
	ds_read_b128 v[188:191], v155 offset:33792
	ds_read_b128 v[192:195], v155 offset:34816
	ds_read_b128 v[196:199], v155 offset:35840
	ds_read_b128 v[200:203], v155 offset:36864
	ds_read_b128 v[204:207], v155 offset:37888
	ds_read_b128 v[208:211], v155 offset:38912
	ds_read_b128 v[212:215], v155 offset:39936
	s_add_i32 m0, s29, 0x4000
	s_nop 0
	global_load_lds_dwordx4 v128, s[98:99]
	s_add_i32 m0, s29, 0x6000
	s_nop 0
	global_load_lds_dwordx4 v132, s[98:99]
	s_waitcnt vmcnt(8)
	s_waitcnt lgkmcnt(0)
	s_barrier
	s_setprio 1
	v_mfma_f32_16x16x32_bf16 v[124:127], v[144:147], v[184:187], v[124:127]
	v_mfma_f32_16x16x32_bf16 v[120:123], v[160:163], v[184:187], v[120:123]
	v_mfma_f32_16x16x32_bf16 v[108:111], v[144:147], v[192:195], v[108:111]
	v_mfma_f32_16x16x32_bf16 v[104:107], v[160:163], v[192:195], v[104:107]
	v_mfma_f32_16x16x32_bf16 v[92:95], v[144:147], v[200:203], v[92:95]
	v_mfma_f32_16x16x32_bf16 v[88:91], v[160:163], v[200:203], v[88:91]
	v_mfma_f32_16x16x32_bf16 v[76:79], v[144:147], v[208:211], v[76:79]
	v_mfma_f32_16x16x32_bf16 v[72:75], v[160:163], v[208:211], v[72:75]
	v_mfma_f32_16x16x32_bf16 v[124:127], v[156:159], v[188:191], v[124:127]
	v_mfma_f32_16x16x32_bf16 v[120:123], v[164:167], v[188:191], v[120:123]
	v_mfma_f32_16x16x32_bf16 v[108:111], v[156:159], v[196:199], v[108:111]
	v_mfma_f32_16x16x32_bf16 v[104:107], v[164:167], v[196:199], v[104:107]
	v_mfma_f32_16x16x32_bf16 v[92:95], v[156:159], v[204:207], v[92:95]
	v_mfma_f32_16x16x32_bf16 v[88:91], v[164:167], v[204:207], v[88:91]
	v_mfma_f32_16x16x32_bf16 v[76:79], v[156:159], v[212:215], v[76:79]
	v_mfma_f32_16x16x32_bf16 v[72:75], v[164:167], v[212:215], v[72:75]
	v_mfma_f32_16x16x32_bf16 v[116:119], v[168:171], v[184:187], v[116:119]
	v_mfma_f32_16x16x32_bf16 v[112:115], v[176:179], v[184:187], v[112:115]
	v_mfma_f32_16x16x32_bf16 v[100:103], v[168:171], v[192:195], v[100:103]
	v_mfma_f32_16x16x32_bf16 v[96:99], v[176:179], v[192:195], v[96:99]
	v_mfma_f32_16x16x32_bf16 v[84:87], v[168:171], v[200:203], v[84:87]
	v_mfma_f32_16x16x32_bf16 v[80:83], v[176:179], v[200:203], v[80:83]
	v_mfma_f32_16x16x32_bf16 v[68:71], v[168:171], v[208:211], v[68:71]
	v_mfma_f32_16x16x32_bf16 v[64:67], v[176:179], v[208:211], v[64:67]
	v_mfma_f32_16x16x32_bf16 v[116:119], v[172:175], v[188:191], v[116:119]
	v_mfma_f32_16x16x32_bf16 v[112:115], v[180:183], v[188:191], v[112:115]
	v_mfma_f32_16x16x32_bf16 v[100:103], v[172:175], v[196:199], v[100:103]
	v_mfma_f32_16x16x32_bf16 v[96:99], v[180:183], v[196:199], v[96:99]
	v_mfma_f32_16x16x32_bf16 v[84:87], v[172:175], v[204:207], v[84:87]
	v_mfma_f32_16x16x32_bf16 v[80:83], v[180:183], v[204:207], v[80:83]
	v_mfma_f32_16x16x32_bf16 v[68:71], v[172:175], v[212:215], v[68:71]
	v_mfma_f32_16x16x32_bf16 v[64:67], v[180:183], v[212:215], v[64:67]
	s_setprio 0
	s_barrier
	s_add_u32 s100, s74, 0x80
	s_addc_u32 s101, s75, 0
	s_add_u32 s42, s74, 0x100080
	s_addc_u32 s43, s75, 0
	s_add_u32 s98, s30, 0x80
	s_addc_u32 s99, s31, 0
	ds_read_b128 v[184:187], v155 offset:49152
	ds_read_b128 v[188:191], v155 offset:50176
	ds_read_b128 v[192:195], v155 offset:51200
	ds_read_b128 v[196:199], v155 offset:52224
	ds_read_b128 v[200:203], v155 offset:53248
	ds_read_b128 v[204:207], v155 offset:54272
	ds_read_b128 v[208:211], v155 offset:55296
	ds_read_b128 v[212:215], v155 offset:56320
	s_add_i32 m0, s29, 0x18000
	s_nop 0
	global_load_lds_dwordx4 v130, s[100:101]
	s_add_i32 m0, s29, 0x1a000
	s_nop 0
	global_load_lds_dwordx4 v134, s[100:101]
	s_add_i32 m0, s29, 0x1c000
	s_nop 0
	global_load_lds_dwordx4 v130, s[42:43]
	s_add_i32 m0, s29, 0x1e000
	s_nop 0
	global_load_lds_dwordx4 v134, s[42:43]
	s_add_i32 m0, s29, 0x8000
	s_nop 0
	global_load_lds_dwordx4 v128, s[98:99]
	s_add_i32 m0, s29, 0xa000
	s_nop 0
	global_load_lds_dwordx4 v132, s[98:99]
	s_waitcnt vmcnt(8)
	s_waitcnt lgkmcnt(0)
	s_barrier
	s_setprio 1
	v_mfma_f32_16x16x32_bf16 v[60:63], v[144:147], v[184:187], v[60:63]
	v_mfma_f32_16x16x32_bf16 v[56:59], v[160:163], v[184:187], v[56:59]
	v_mfma_f32_16x16x32_bf16 v[44:47], v[144:147], v[192:195], v[44:47]
	v_mfma_f32_16x16x32_bf16 v[40:43], v[160:163], v[192:195], v[40:43]
	v_mfma_f32_16x16x32_bf16 v[28:31], v[144:147], v[200:203], v[28:31]
	v_mfma_f32_16x16x32_bf16 v[24:27], v[160:163], v[200:203], v[24:27]
	v_mfma_f32_16x16x32_bf16 v[12:15], v[144:147], v[208:211], v[12:15]
	v_mfma_f32_16x16x32_bf16 v[8:11], v[160:163], v[208:211], v[8:11]
	v_mfma_f32_16x16x32_bf16 v[60:63], v[156:159], v[188:191], v[60:63]
	v_mfma_f32_16x16x32_bf16 v[56:59], v[164:167], v[188:191], v[56:59]
	v_mfma_f32_16x16x32_bf16 v[44:47], v[156:159], v[196:199], v[44:47]
	v_mfma_f32_16x16x32_bf16 v[40:43], v[164:167], v[196:199], v[40:43]
	v_mfma_f32_16x16x32_bf16 v[28:31], v[156:159], v[204:207], v[28:31]
	v_mfma_f32_16x16x32_bf16 v[24:27], v[164:167], v[204:207], v[24:27]
	v_mfma_f32_16x16x32_bf16 v[12:15], v[156:159], v[212:215], v[12:15]
	v_mfma_f32_16x16x32_bf16 v[8:11], v[164:167], v[212:215], v[8:11]
	v_mfma_f32_16x16x32_bf16 v[52:55], v[168:171], v[184:187], v[52:55]
	v_mfma_f32_16x16x32_bf16 v[48:51], v[176:179], v[184:187], v[48:51]
	v_mfma_f32_16x16x32_bf16 v[36:39], v[168:171], v[192:195], v[36:39]
	v_mfma_f32_16x16x32_bf16 v[32:35], v[176:179], v[192:195], v[32:35]
	v_mfma_f32_16x16x32_bf16 v[20:23], v[168:171], v[200:203], v[20:23]
	v_mfma_f32_16x16x32_bf16 v[16:19], v[176:179], v[200:203], v[16:19]
	v_mfma_f32_16x16x32_bf16 v[4:7], v[168:171], v[208:211], v[4:7]
	v_mfma_f32_16x16x32_bf16 v[0:3], v[176:179], v[208:211], v[0:3]
	v_mfma_f32_16x16x32_bf16 v[52:55], v[172:175], v[188:191], v[52:55]
	v_mfma_f32_16x16x32_bf16 v[48:51], v[180:183], v[188:191], v[48:51]
	v_mfma_f32_16x16x32_bf16 v[36:39], v[172:175], v[196:199], v[36:39]
	v_mfma_f32_16x16x32_bf16 v[32:35], v[180:183], v[196:199], v[32:35]
	v_mfma_f32_16x16x32_bf16 v[20:23], v[172:175], v[204:207], v[20:23]
	v_mfma_f32_16x16x32_bf16 v[16:19], v[180:183], v[204:207], v[16:19]
	v_mfma_f32_16x16x32_bf16 v[4:7], v[172:175], v[212:215], v[4:7]
	v_mfma_f32_16x16x32_bf16 v[0:3], v[180:183], v[212:215], v[0:3]
	s_setprio 0
	s_barrier
	s_add_i32 s41, s41, 2
	s_add_u32 s72, s72, 0x100
	s_addc_u32 s73, s73, 0
	s_add_u32 s39, s39, 0x100
	s_addc_u32 s40, s40, 0
	s_cmp_gt_u32 s41, 61
	s_cbranch_scc0 .LBB0_182
	s_and_b64 vcc, exec, s[6:7]
	s_cbranch_vccz .LBB0_185
	s_barrier

.LBB0_401:
	ds_read_b128 v[142:145], v169 offset:0
	ds_read_b128 v[146:149], v169 offset:1024
	ds_read_b128 v[150:153], v169 offset:2048
	ds_read_b128 v[154:157], v169 offset:3072
	ds_read_b128 v[158:161], v170 offset:0
	ds_read_b128 v[162:165], v170 offset:1024
	ds_read_b128 v[172:175], v170 offset:2048
	ds_read_b128 v[176:179], v170 offset:3072
	s_add_i32 s38, s30, 2
	s_add_u32 s46, s44, 0x100
	s_addc_u32 s47, s45, 0
	s_cmp_eq_u32 s17, s30
	s_cselect_b32 s30, s34, s46
	s_cselect_b32 s31, s35, s47
	s_cselect_b32 s53, s41, s37
	s_cselect_b32 s52, s40, s36
	ds_read_b128 v[180:183], v171 offset:0
	ds_read_b128 v[184:187], v171 offset:1024
	ds_read_b128 v[188:191], v171 offset:2048
	ds_read_b128 v[192:195], v171 offset:3072
	ds_read_b128 v[196:199], v171 offset:4096
	ds_read_b128 v[200:203], v171 offset:5120
	ds_read_b128 v[204:207], v171 offset:6144
	ds_read_b128 v[208:211], v171 offset:7168
	s_add_i32 m0, s60, 0xc000
	s_nop 0
	global_load_lds_dwordx4 v136, s[44:45]
	s_add_i32 m0, s60, 0xe000
	s_nop 0
	global_load_lds_dwordx4 v138, s[44:45]
	s_waitcnt vmcnt(8)
	s_waitcnt lgkmcnt(0)
	s_barrier
	s_setprio 1
	v_mfma_f32_16x16x32_bf16 v[124:127], v[142:145], v[180:183], v[124:127]
	v_mfma_f32_16x16x32_bf16 v[120:123], v[150:153], v[180:183], v[120:123]
	v_mfma_f32_16x16x32_bf16 v[108:111], v[142:145], v[188:191], v[108:111]
	v_mfma_f32_16x16x32_bf16 v[104:107], v[150:153], v[188:191], v[104:107]
	v_mfma_f32_16x16x32_bf16 v[92:95], v[142:145], v[196:199], v[92:95]
	v_mfma_f32_16x16x32_bf16 v[88:91], v[150:153], v[196:199], v[88:91]
	v_mfma_f32_16x16x32_bf16 v[76:79], v[142:145], v[204:207], v[76:79]
	v_mfma_f32_16x16x32_bf16 v[72:75], v[150:153], v[204:207], v[72:75]
	v_mfma_f32_16x16x32_bf16 v[124:127], v[146:149], v[184:187], v[124:127]
	v_mfma_f32_16x16x32_bf16 v[120:123], v[154:157], v[184:187], v[120:123]
	v_mfma_f32_16x16x32_bf16 v[108:111], v[146:149], v[192:195], v[108:111]
	v_mfma_f32_16x16x32_bf16 v[104:107], v[154:157], v[192:195], v[104:107]
	v_mfma_f32_16x16x32_bf16 v[92:95], v[146:149], v[200:203], v[92:95]
	v_mfma_f32_16x16x32_bf16 v[88:91], v[154:157], v[200:203], v[88:91]
	v_mfma_f32_16x16x32_bf16 v[76:79], v[146:149], v[208:211], v[76:79]
	v_mfma_f32_16x16x32_bf16 v[72:75], v[154:157], v[208:211], v[72:75]
	v_mfma_f32_16x16x32_bf16 v[116:119], v[158:161], v[180:183], v[116:119]
	v_mfma_f32_16x16x32_bf16 v[112:115], v[172:175], v[180:183], v[112:115]
	v_mfma_f32_16x16x32_bf16 v[100:103], v[158:161], v[188:191], v[100:103]
	v_mfma_f32_16x16x32_bf16 v[96:99], v[172:175], v[188:191], v[96:99]
	v_mfma_f32_16x16x32_bf16 v[84:87], v[158:161], v[196:199], v[84:87]
	v_mfma_f32_16x16x32_bf16 v[80:83], v[172:175], v[196:199], v[80:83]
	v_mfma_f32_16x16x32_bf16 v[68:71], v[158:161], v[204:207], v[68:71]
	v_mfma_f32_16x16x32_bf16 v[64:67], v[172:175], v[204:207], v[64:67]
	v_mfma_f32_16x16x32_bf16 v[116:119], v[162:165], v[184:187], v[116:119]
	v_mfma_f32_16x16x32_bf16 v[112:115], v[176:179], v[184:187], v[112:115]
	v_mfma_f32_16x16x32_bf16 v[100:103], v[162:165], v[192:195], v[100:103]
	v_mfma_f32_16x16x32_bf16 v[96:99], v[176:179], v[192:195], v[96:99]
	v_mfma_f32_16x16x32_bf16 v[84:87], v[162:165], v[200:203], v[84:87]
	v_mfma_f32_16x16x32_bf16 v[80:83], v[176:179], v[200:203], v[80:83]
	v_mfma_f32_16x16x32_bf16 v[68:71], v[162:165], v[208:211], v[68:71]
	v_mfma_f32_16x16x32_bf16 v[64:67], v[176:179], v[208:211], v[64:67]
	s_setprio 0
	s_barrier
	s_add_u32 s42, s52, 0x2b0000
	s_addc_u32 s43, s53, 0
	ds_read_b128 v[180:183], v171 offset:16384
	ds_read_b128 v[184:187], v171 offset:17408
	ds_read_b128 v[188:191], v171 offset:18432
	ds_read_b128 v[192:195], v171 offset:19456
	ds_read_b128 v[196:199], v171 offset:20480
	ds_read_b128 v[200:203], v171 offset:21504
	ds_read_b128 v[204:207], v171 offset:22528
	ds_read_b128 v[208:211], v171 offset:23552
	s_add_i32 m0, s60, 0x10000
	s_nop 0
	global_load_lds_dwordx4 v130, s[52:53]
	s_add_i32 m0, s60, 0x12000
	s_nop 0
	global_load_lds_dwordx4 v134, s[52:53]
	s_add_i32 m0, s60, 0x14000
	s_nop 0
	global_load_lds_dwordx4 v130, s[42:43]
	s_add_i32 m0, s60, 0x16000
	s_nop 0
	global_load_lds_dwordx4 v134, s[42:43]
	s_add_i32 m0, s60, 0x0
	s_nop 0
	global_load_lds_dwordx4 v128, s[30:31]
	s_add_i32 m0, s60, 0x2000
	s_nop 0
	global_load_lds_dwordx4 v132, s[30:31]
	s_waitcnt vmcnt(8)
	s_waitcnt lgkmcnt(0)
	s_barrier
	s_setprio 1
	v_mfma_f32_16x16x32_bf16 v[60:63], v[142:145], v[180:183], v[60:63]
	v_mfma_f32_16x16x32_bf16 v[56:59], v[150:153], v[180:183], v[56:59]
	v_mfma_f32_16x16x32_bf16 v[44:47], v[142:145], v[188:191], v[44:47]
	v_mfma_f32_16x16x32_bf16 v[40:43], v[150:153], v[188:191], v[40:43]
	v_mfma_f32_16x16x32_bf16 v[28:31], v[142:145], v[196:199], v[28:31]
	v_mfma_f32_16x16x32_bf16 v[24:27], v[150:153], v[196:199], v[24:27]
	v_mfma_f32_16x16x32_bf16 v[12:15], v[142:145], v[204:207], v[12:15]
	v_mfma_f32_16x16x32_bf16 v[8:11], v[150:153], v[204:207], v[8:11]
	v_mfma_f32_16x16x32_bf16 v[60:63], v[146:149], v[184:187], v[60:63]
	v_mfma_f32_16x16x32_bf16 v[56:59], v[154:157], v[184:187], v[56:59]
	v_mfma_f32_16x16x32_bf16 v[44:47], v[146:149], v[192:195], v[44:47]
	v_mfma_f32_16x16x32_bf16 v[40:43], v[154:157], v[192:195], v[40:43]
	v_mfma_f32_16x16x32_bf16 v[28:31], v[146:149], v[200:203], v[28:31]
	v_mfma_f32_16x16x32_bf16 v[24:27], v[154:157], v[200:203], v[24:27]
	v_mfma_f32_16x16x32_bf16 v[12:15], v[146:149], v[208:211], v[12:15]
	v_mfma_f32_16x16x32_bf16 v[8:11], v[154:157], v[208:211], v[8:11]
	v_mfma_f32_16x16x32_bf16 v[52:55], v[158:161], v[180:183], v[52:55]
	v_mfma_f32_16x16x32_bf16 v[48:51], v[172:175], v[180:183], v[48:51]
	v_mfma_f32_16x16x32_bf16 v[36:39], v[158:161], v[188:191], v[36:39]
	v_mfma_f32_16x16x32_bf16 v[32:35], v[172:175], v[188:191], v[32:35]
	v_mfma_f32_16x16x32_bf16 v[20:23], v[158:161], v[196:199], v[20:23]
	v_mfma_f32_16x16x32_bf16 v[16:19], v[172:175], v[196:199], v[16:19]
	v_mfma_f32_16x16x32_bf16 v[4:7], v[158:161], v[204:207], v[4:7]
	v_mfma_f32_16x16x32_bf16 v[0:3], v[172:175], v[204:207], v[0:3]
	v_mfma_f32_16x16x32_bf16 v[52:55], v[162:165], v[184:187], v[52:55]
	v_mfma_f32_16x16x32_bf16 v[48:51], v[176:179], v[184:187], v[48:51]
	v_mfma_f32_16x16x32_bf16 v[36:39], v[162:165], v[192:195], v[36:39]
	v_mfma_f32_16x16x32_bf16 v[32:35], v[176:179], v[192:195], v[32:35]
	v_mfma_f32_16x16x32_bf16 v[20:23], v[162:165], v[200:203], v[20:23]
	v_mfma_f32_16x16x32_bf16 v[16:19], v[176:179], v[200:203], v[16:19]
	v_mfma_f32_16x16x32_bf16 v[4:7], v[162:165], v[208:211], v[4:7]
	v_mfma_f32_16x16x32_bf16 v[0:3], v[176:179], v[208:211], v[0:3]
	s_setprio 0
	s_barrier
	s_add_u32 s98, s30, 0x2b0000
	s_addc_u32 s99, s31, 0
	ds_read_b128 v[142:145], v169 offset:32768
	ds_read_b128 v[146:149], v169 offset:33792
	ds_read_b128 v[150:153], v169 offset:34816
	ds_read_b128 v[154:157], v169 offset:35840
	ds_read_b128 v[158:161], v170 offset:32768
	ds_read_b128 v[162:165], v170 offset:33792
	ds_read_b128 v[172:175], v170 offset:34816
	ds_read_b128 v[176:179], v170 offset:35840
	ds_read_b128 v[180:183], v171 offset:32768
	ds_read_b128 v[184:187], v171 offset:33792
	ds_read_b128 v[188:191], v171 offset:34816
	ds_read_b128 v[192:195], v171 offset:35840
	ds_read_b128 v[196:199], v171 offset:36864
	ds_read_b128 v[200:203], v171 offset:37888
	ds_read_b128 v[204:207], v171 offset:38912
	ds_read_b128 v[208:211], v171 offset:39936
	s_add_i32 m0, s60, 0x4000
	s_nop 0
	global_load_lds_dwordx4 v128, s[98:99]
	s_add_i32 m0, s60, 0x6000
	s_nop 0
	global_load_lds_dwordx4 v132, s[98:99]
	s_waitcnt vmcnt(8)
	s_waitcnt lgkmcnt(0)
	s_barrier
	s_setprio 1
	v_mfma_f32_16x16x32_bf16 v[124:127], v[142:145], v[180:183], v[124:127]
	v_mfma_f32_16x16x32_bf16 v[120:123], v[150:153], v[180:183], v[120:123]
	v_mfma_f32_16x16x32_bf16 v[108:111], v[142:145], v[188:191], v[108:111]
	v_mfma_f32_16x16x32_bf16 v[104:107], v[150:153], v[188:191], v[104:107]
	v_mfma_f32_16x16x32_bf16 v[92:95], v[142:145], v[196:199], v[92:95]
	v_mfma_f32_16x16x32_bf16 v[88:91], v[150:153], v[196:199], v[88:91]
	v_mfma_f32_16x16x32_bf16 v[76:79], v[142:145], v[204:207], v[76:79]
	v_mfma_f32_16x16x32_bf16 v[72:75], v[150:153], v[204:207], v[72:75]
	v_mfma_f32_16x16x32_bf16 v[124:127], v[146:149], v[184:187], v[124:127]
	v_mfma_f32_16x16x32_bf16 v[120:123], v[154:157], v[184:187], v[120:123]
	v_mfma_f32_16x16x32_bf16 v[108:111], v[146:149], v[192:195], v[108:111]
	v_mfma_f32_16x16x32_bf16 v[104:107], v[154:157], v[192:195], v[104:107]
	v_mfma_f32_16x16x32_bf16 v[92:95], v[146:149], v[200:203], v[92:95]
	v_mfma_f32_16x16x32_bf16 v[88:91], v[154:157], v[200:203], v[88:91]
	v_mfma_f32_16x16x32_bf16 v[76:79], v[146:149], v[208:211], v[76:79]
	v_mfma_f32_16x16x32_bf16 v[72:75], v[154:157], v[208:211], v[72:75]
	v_mfma_f32_16x16x32_bf16 v[116:119], v[158:161], v[180:183], v[116:119]
	v_mfma_f32_16x16x32_bf16 v[112:115], v[172:175], v[180:183], v[112:115]
	v_mfma_f32_16x16x32_bf16 v[100:103], v[158:161], v[188:191], v[100:103]
	v_mfma_f32_16x16x32_bf16 v[96:99], v[172:175], v[188:191], v[96:99]
	v_mfma_f32_16x16x32_bf16 v[84:87], v[158:161], v[196:199], v[84:87]
	v_mfma_f32_16x16x32_bf16 v[80:83], v[172:175], v[196:199], v[80:83]
	v_mfma_f32_16x16x32_bf16 v[68:71], v[158:161], v[204:207], v[68:71]
	v_mfma_f32_16x16x32_bf16 v[64:67], v[172:175], v[204:207], v[64:67]
	v_mfma_f32_16x16x32_bf16 v[116:119], v[162:165], v[184:187], v[116:119]
	v_mfma_f32_16x16x32_bf16 v[112:115], v[176:179], v[184:187], v[112:115]
	v_mfma_f32_16x16x32_bf16 v[100:103], v[162:165], v[192:195], v[100:103]
	v_mfma_f32_16x16x32_bf16 v[96:99], v[176:179], v[192:195], v[96:99]
	v_mfma_f32_16x16x32_bf16 v[84:87], v[162:165], v[200:203], v[84:87]
	v_mfma_f32_16x16x32_bf16 v[80:83], v[176:179], v[200:203], v[80:83]
	v_mfma_f32_16x16x32_bf16 v[68:71], v[162:165], v[208:211], v[68:71]
	v_mfma_f32_16x16x32_bf16 v[64:67], v[176:179], v[208:211], v[64:67]
	s_setprio 0
	s_barrier
	s_add_u32 s100, s52, 0x80
	s_addc_u32 s101, s53, 0
	s_add_u32 s42, s52, 0x2b0080
	s_addc_u32 s43, s53, 0
	s_add_u32 s98, s30, 0x80
	s_addc_u32 s99, s31, 0
	ds_read_b128 v[180:183], v171 offset:49152
	ds_read_b128 v[184:187], v171 offset:50176
	ds_read_b128 v[188:191], v171 offset:51200
	ds_read_b128 v[192:195], v171 offset:52224
	ds_read_b128 v[196:199], v171 offset:53248
	ds_read_b128 v[200:203], v171 offset:54272
	ds_read_b128 v[204:207], v171 offset:55296
	ds_read_b128 v[208:211], v171 offset:56320
	s_add_i32 m0, s60, 0x18000
	s_nop 0
	global_load_lds_dwordx4 v130, s[100:101]
	s_add_i32 m0, s60, 0x1a000
	s_nop 0
	global_load_lds_dwordx4 v134, s[100:101]
	s_add_i32 m0, s60, 0x1c000
	s_nop 0
	global_load_lds_dwordx4 v130, s[42:43]
	s_add_i32 m0, s60, 0x1e000
	s_nop 0
	global_load_lds_dwordx4 v134, s[42:43]
	s_add_i32 m0, s60, 0x8000
	s_nop 0
	global_load_lds_dwordx4 v128, s[98:99]
	s_add_i32 m0, s60, 0xa000
	s_nop 0
	global_load_lds_dwordx4 v132, s[98:99]
	s_waitcnt vmcnt(8)
	s_waitcnt lgkmcnt(0)
	s_barrier
	s_setprio 1
	v_mfma_f32_16x16x32_bf16 v[60:63], v[142:145], v[180:183], v[60:63]
	v_mfma_f32_16x16x32_bf16 v[56:59], v[150:153], v[180:183], v[56:59]
	v_mfma_f32_16x16x32_bf16 v[44:47], v[142:145], v[188:191], v[44:47]
	v_mfma_f32_16x16x32_bf16 v[40:43], v[150:153], v[188:191], v[40:43]
	v_mfma_f32_16x16x32_bf16 v[28:31], v[142:145], v[196:199], v[28:31]
	v_mfma_f32_16x16x32_bf16 v[24:27], v[150:153], v[196:199], v[24:27]
	v_mfma_f32_16x16x32_bf16 v[12:15], v[142:145], v[204:207], v[12:15]
	v_mfma_f32_16x16x32_bf16 v[8:11], v[150:153], v[204:207], v[8:11]
	v_mfma_f32_16x16x32_bf16 v[60:63], v[146:149], v[184:187], v[60:63]
	v_mfma_f32_16x16x32_bf16 v[56:59], v[154:157], v[184:187], v[56:59]
	v_mfma_f32_16x16x32_bf16 v[44:47], v[146:149], v[192:195], v[44:47]
	v_mfma_f32_16x16x32_bf16 v[40:43], v[154:157], v[192:195], v[40:43]
	v_mfma_f32_16x16x32_bf16 v[28:31], v[146:149], v[200:203], v[28:31]
	v_mfma_f32_16x16x32_bf16 v[24:27], v[154:157], v[200:203], v[24:27]
	v_mfma_f32_16x16x32_bf16 v[12:15], v[146:149], v[208:211], v[12:15]
	v_mfma_f32_16x16x32_bf16 v[8:11], v[154:157], v[208:211], v[8:11]
	v_mfma_f32_16x16x32_bf16 v[52:55], v[158:161], v[180:183], v[52:55]
	v_mfma_f32_16x16x32_bf16 v[48:51], v[172:175], v[180:183], v[48:51]
	v_mfma_f32_16x16x32_bf16 v[36:39], v[158:161], v[188:191], v[36:39]
	v_mfma_f32_16x16x32_bf16 v[32:35], v[172:175], v[188:191], v[32:35]
	v_mfma_f32_16x16x32_bf16 v[20:23], v[158:161], v[196:199], v[20:23]
	v_mfma_f32_16x16x32_bf16 v[16:19], v[172:175], v[196:199], v[16:19]
	v_mfma_f32_16x16x32_bf16 v[4:7], v[158:161], v[204:207], v[4:7]
	v_mfma_f32_16x16x32_bf16 v[0:3], v[172:175], v[204:207], v[0:3]
	v_mfma_f32_16x16x32_bf16 v[52:55], v[162:165], v[184:187], v[52:55]
	v_mfma_f32_16x16x32_bf16 v[48:51], v[176:179], v[184:187], v[48:51]
	v_mfma_f32_16x16x32_bf16 v[36:39], v[162:165], v[192:195], v[36:39]
	v_mfma_f32_16x16x32_bf16 v[32:35], v[176:179], v[192:195], v[32:35]
	v_mfma_f32_16x16x32_bf16 v[20:23], v[162:165], v[200:203], v[20:23]
	v_mfma_f32_16x16x32_bf16 v[16:19], v[176:179], v[200:203], v[16:19]
	v_mfma_f32_16x16x32_bf16 v[4:7], v[162:165], v[208:211], v[4:7]
	v_mfma_f32_16x16x32_bf16 v[0:3], v[176:179], v[208:211], v[0:3]
	s_setprio 0
	s_barrier
	s_add_u32 s36, s36, 0x100
	s_addc_u32 s37, s37, 0
	s_cmp_ge_i32 s38, s87
	s_mov_b64 s[44:45], s[46:47]
	s_mov_b32 s30, s38
	s_cbranch_scc0 .LBB0_401
	s_and_b64 vcc, exec, s[12:13]
	s_cbranch_vccz .LBB0_404

.LBB0_1299:
	ds_read_b128 v[144:147], v153 offset:0
	ds_read_b128 v[156:159], v153 offset:1024
	ds_read_b128 v[160:163], v153 offset:2048
	ds_read_b128 v[164:167], v153 offset:3072
	ds_read_b128 v[168:171], v154 offset:0
	ds_read_b128 v[172:175], v154 offset:1024
	ds_read_b128 v[176:179], v154 offset:2048
	ds_read_b128 v[180:183], v154 offset:3072
	s_add_u32 s36, s34, 0xfff00080
	s_addc_u32 s37, s35, -1
	s_cmp_eq_u32 s57, 60
	s_cselect_b32 s39, s13, s37
	s_cselect_b32 s38, s53, s36
	s_cselect_b32 s37, s11, s56
	s_cselect_b32 s36, s54, s55
	ds_read_b128 v[184:187], v155 offset:0
	ds_read_b128 v[188:191], v155 offset:1024
	ds_read_b128 v[192:195], v155 offset:2048
	ds_read_b128 v[196:199], v155 offset:3072
	ds_read_b128 v[202:205], v155 offset:4096
	ds_read_b128 v[206:209], v155 offset:5120
	ds_read_b128 v[210:213], v155 offset:6144
	ds_read_b128 v[214:217], v155 offset:7168
	s_add_i32 m0, s31, 0xc000
	s_nop 0
	global_load_lds_dwordx4 v136, s[34:35]
	s_add_i32 m0, s31, 0xe000
	s_nop 0
	global_load_lds_dwordx4 v138, s[34:35]
	s_waitcnt vmcnt(8)
	s_waitcnt lgkmcnt(0)
	s_barrier
	s_setprio 1
	v_mfma_f32_16x16x32_bf16 v[124:127], v[144:147], v[184:187], v[124:127]
	v_mfma_f32_16x16x32_bf16 v[120:123], v[160:163], v[184:187], v[120:123]
	v_mfma_f32_16x16x32_bf16 v[108:111], v[144:147], v[192:195], v[108:111]
	v_mfma_f32_16x16x32_bf16 v[104:107], v[160:163], v[192:195], v[104:107]
	v_mfma_f32_16x16x32_bf16 v[92:95], v[144:147], v[202:205], v[92:95]
	v_mfma_f32_16x16x32_bf16 v[88:91], v[160:163], v[202:205], v[88:91]
	v_mfma_f32_16x16x32_bf16 v[76:79], v[144:147], v[210:213], v[76:79]
	v_mfma_f32_16x16x32_bf16 v[72:75], v[160:163], v[210:213], v[72:75]
	v_mfma_f32_16x16x32_bf16 v[124:127], v[156:159], v[188:191], v[124:127]
	v_mfma_f32_16x16x32_bf16 v[120:123], v[164:167], v[188:191], v[120:123]
	v_mfma_f32_16x16x32_bf16 v[108:111], v[156:159], v[196:199], v[108:111]
	v_mfma_f32_16x16x32_bf16 v[104:107], v[164:167], v[196:199], v[104:107]
	v_mfma_f32_16x16x32_bf16 v[92:95], v[156:159], v[206:209], v[92:95]
	v_mfma_f32_16x16x32_bf16 v[88:91], v[164:167], v[206:209], v[88:91]
	v_mfma_f32_16x16x32_bf16 v[76:79], v[156:159], v[214:217], v[76:79]
	v_mfma_f32_16x16x32_bf16 v[72:75], v[164:167], v[214:217], v[72:75]
	v_mfma_f32_16x16x32_bf16 v[116:119], v[168:171], v[184:187], v[116:119]
	v_mfma_f32_16x16x32_bf16 v[112:115], v[176:179], v[184:187], v[112:115]
	v_mfma_f32_16x16x32_bf16 v[100:103], v[168:171], v[192:195], v[100:103]
	v_mfma_f32_16x16x32_bf16 v[96:99], v[176:179], v[192:195], v[96:99]
	v_mfma_f32_16x16x32_bf16 v[84:87], v[168:171], v[202:205], v[84:87]
	v_mfma_f32_16x16x32_bf16 v[80:83], v[176:179], v[202:205], v[80:83]
	v_mfma_f32_16x16x32_bf16 v[68:71], v[168:171], v[210:213], v[68:71]
	v_mfma_f32_16x16x32_bf16 v[64:67], v[176:179], v[210:213], v[64:67]
	v_mfma_f32_16x16x32_bf16 v[116:119], v[172:175], v[188:191], v[116:119]
	v_mfma_f32_16x16x32_bf16 v[112:115], v[180:183], v[188:191], v[112:115]
	v_mfma_f32_16x16x32_bf16 v[100:103], v[172:175], v[196:199], v[100:103]
	v_mfma_f32_16x16x32_bf16 v[96:99], v[180:183], v[196:199], v[96:99]
	v_mfma_f32_16x16x32_bf16 v[84:87], v[172:175], v[206:209], v[84:87]
	v_mfma_f32_16x16x32_bf16 v[80:83], v[180:183], v[206:209], v[80:83]
	v_mfma_f32_16x16x32_bf16 v[68:71], v[172:175], v[214:217], v[68:71]
	v_mfma_f32_16x16x32_bf16 v[64:67], v[180:183], v[214:217], v[64:67]
	s_setprio 0
	s_barrier
	s_add_u32 s58, s36, 0x100000
	s_addc_u32 s59, s37, 0
	ds_read_b128 v[184:187], v155 offset:16384
	ds_read_b128 v[188:191], v155 offset:17408
	ds_read_b128 v[192:195], v155 offset:18432
	ds_read_b128 v[196:199], v155 offset:19456
	ds_read_b128 v[202:205], v155 offset:20480
	ds_read_b128 v[206:209], v155 offset:21504
	ds_read_b128 v[210:213], v155 offset:22528
	ds_read_b128 v[214:217], v155 offset:23552
	s_add_i32 m0, s31, 0x10000
	s_nop 0
	global_load_lds_dwordx4 v130, s[36:37]
	s_add_i32 m0, s31, 0x12000
	s_nop 0
	global_load_lds_dwordx4 v134, s[36:37]
	s_add_i32 m0, s31, 0x14000
	s_nop 0
	global_load_lds_dwordx4 v130, s[58:59]
	s_add_i32 m0, s31, 0x16000
	s_nop 0
	global_load_lds_dwordx4 v134, s[58:59]
	s_add_i32 m0, s31, 0x0
	s_nop 0
	global_load_lds_dwordx4 v128, s[38:39]
	s_add_i32 m0, s31, 0x2000
	s_nop 0
	global_load_lds_dwordx4 v132, s[38:39]
	s_waitcnt vmcnt(8)
	s_waitcnt lgkmcnt(0)
	s_barrier
	s_setprio 1
	v_mfma_f32_16x16x32_bf16 v[60:63], v[144:147], v[184:187], v[60:63]
	v_mfma_f32_16x16x32_bf16 v[56:59], v[160:163], v[184:187], v[56:59]
	v_mfma_f32_16x16x32_bf16 v[44:47], v[144:147], v[192:195], v[44:47]
	v_mfma_f32_16x16x32_bf16 v[40:43], v[160:163], v[192:195], v[40:43]
	v_mfma_f32_16x16x32_bf16 v[28:31], v[144:147], v[202:205], v[28:31]
	v_mfma_f32_16x16x32_bf16 v[24:27], v[160:163], v[202:205], v[24:27]
	v_mfma_f32_16x16x32_bf16 v[12:15], v[144:147], v[210:213], v[12:15]
	v_mfma_f32_16x16x32_bf16 v[8:11], v[160:163], v[210:213], v[8:11]
	v_mfma_f32_16x16x32_bf16 v[60:63], v[156:159], v[188:191], v[60:63]
	v_mfma_f32_16x16x32_bf16 v[56:59], v[164:167], v[188:191], v[56:59]
	v_mfma_f32_16x16x32_bf16 v[44:47], v[156:159], v[196:199], v[44:47]
	v_mfma_f32_16x16x32_bf16 v[40:43], v[164:167], v[196:199], v[40:43]
	v_mfma_f32_16x16x32_bf16 v[28:31], v[156:159], v[206:209], v[28:31]
	v_mfma_f32_16x16x32_bf16 v[24:27], v[164:167], v[206:209], v[24:27]
	v_mfma_f32_16x16x32_bf16 v[12:15], v[156:159], v[214:217], v[12:15]
	v_mfma_f32_16x16x32_bf16 v[8:11], v[164:167], v[214:217], v[8:11]
	v_mfma_f32_16x16x32_bf16 v[52:55], v[168:171], v[184:187], v[52:55]
	v_mfma_f32_16x16x32_bf16 v[48:51], v[176:179], v[184:187], v[48:51]
	v_mfma_f32_16x16x32_bf16 v[36:39], v[168:171], v[192:195], v[36:39]
	v_mfma_f32_16x16x32_bf16 v[32:35], v[176:179], v[192:195], v[32:35]
	v_mfma_f32_16x16x32_bf16 v[20:23], v[168:171], v[202:205], v[20:23]
	v_mfma_f32_16x16x32_bf16 v[16:19], v[176:179], v[202:205], v[16:19]
	v_mfma_f32_16x16x32_bf16 v[4:7], v[168:171], v[210:213], v[4:7]
	v_mfma_f32_16x16x32_bf16 v[0:3], v[176:179], v[210:213], v[0:3]
	v_mfma_f32_16x16x32_bf16 v[52:55], v[172:175], v[188:191], v[52:55]
	v_mfma_f32_16x16x32_bf16 v[48:51], v[180:183], v[188:191], v[48:51]
	v_mfma_f32_16x16x32_bf16 v[36:39], v[172:175], v[196:199], v[36:39]
	v_mfma_f32_16x16x32_bf16 v[32:35], v[180:183], v[196:199], v[32:35]
	v_mfma_f32_16x16x32_bf16 v[20:23], v[172:175], v[206:209], v[20:23]
	v_mfma_f32_16x16x32_bf16 v[16:19], v[180:183], v[206:209], v[16:19]
	v_mfma_f32_16x16x32_bf16 v[4:7], v[172:175], v[214:217], v[4:7]
	v_mfma_f32_16x16x32_bf16 v[0:3], v[180:183], v[214:217], v[0:3]
	s_setprio 0
	s_barrier
	s_add_u32 s98, s38, 0x100000
	s_addc_u32 s99, s39, 0
	ds_read_b128 v[144:147], v153 offset:32768
	ds_read_b128 v[156:159], v153 offset:33792
	ds_read_b128 v[160:163], v153 offset:34816
	ds_read_b128 v[164:167], v153 offset:35840
	ds_read_b128 v[168:171], v154 offset:32768
	ds_read_b128 v[172:175], v154 offset:33792
	ds_read_b128 v[176:179], v154 offset:34816
	ds_read_b128 v[180:183], v154 offset:35840
	ds_read_b128 v[184:187], v155 offset:32768
	ds_read_b128 v[188:191], v155 offset:33792
	ds_read_b128 v[192:195], v155 offset:34816
	ds_read_b128 v[196:199], v155 offset:35840
	ds_read_b128 v[202:205], v155 offset:36864
	ds_read_b128 v[206:209], v155 offset:37888
	ds_read_b128 v[210:213], v155 offset:38912
	ds_read_b128 v[214:217], v155 offset:39936
	s_add_i32 m0, s31, 0x4000
	s_nop 0
	global_load_lds_dwordx4 v128, s[98:99]
	s_add_i32 m0, s31, 0x6000
	s_nop 0
	global_load_lds_dwordx4 v132, s[98:99]
	s_waitcnt vmcnt(8)
	s_waitcnt lgkmcnt(0)
	s_barrier
	s_setprio 1
	v_mfma_f32_16x16x32_bf16 v[124:127], v[144:147], v[184:187], v[124:127]
	v_mfma_f32_16x16x32_bf16 v[120:123], v[160:163], v[184:187], v[120:123]
	v_mfma_f32_16x16x32_bf16 v[108:111], v[144:147], v[192:195], v[108:111]
	v_mfma_f32_16x16x32_bf16 v[104:107], v[160:163], v[192:195], v[104:107]
	v_mfma_f32_16x16x32_bf16 v[92:95], v[144:147], v[202:205], v[92:95]
	v_mfma_f32_16x16x32_bf16 v[88:91], v[160:163], v[202:205], v[88:91]
	v_mfma_f32_16x16x32_bf16 v[76:79], v[144:147], v[210:213], v[76:79]
	v_mfma_f32_16x16x32_bf16 v[72:75], v[160:163], v[210:213], v[72:75]
	v_mfma_f32_16x16x32_bf16 v[124:127], v[156:159], v[188:191], v[124:127]
	v_mfma_f32_16x16x32_bf16 v[120:123], v[164:167], v[188:191], v[120:123]
	v_mfma_f32_16x16x32_bf16 v[108:111], v[156:159], v[196:199], v[108:111]
	v_mfma_f32_16x16x32_bf16 v[104:107], v[164:167], v[196:199], v[104:107]
	v_mfma_f32_16x16x32_bf16 v[92:95], v[156:159], v[206:209], v[92:95]
	v_mfma_f32_16x16x32_bf16 v[88:91], v[164:167], v[206:209], v[88:91]
	v_mfma_f32_16x16x32_bf16 v[76:79], v[156:159], v[214:217], v[76:79]
	v_mfma_f32_16x16x32_bf16 v[72:75], v[164:167], v[214:217], v[72:75]
	v_mfma_f32_16x16x32_bf16 v[116:119], v[168:171], v[184:187], v[116:119]
	v_mfma_f32_16x16x32_bf16 v[112:115], v[176:179], v[184:187], v[112:115]
	v_mfma_f32_16x16x32_bf16 v[100:103], v[168:171], v[192:195], v[100:103]
	v_mfma_f32_16x16x32_bf16 v[96:99], v[176:179], v[192:195], v[96:99]
	v_mfma_f32_16x16x32_bf16 v[84:87], v[168:171], v[202:205], v[84:87]
	v_mfma_f32_16x16x32_bf16 v[80:83], v[176:179], v[202:205], v[80:83]
	v_mfma_f32_16x16x32_bf16 v[68:71], v[168:171], v[210:213], v[68:71]
	v_mfma_f32_16x16x32_bf16 v[64:67], v[176:179], v[210:213], v[64:67]
	v_mfma_f32_16x16x32_bf16 v[116:119], v[172:175], v[188:191], v[116:119]
	v_mfma_f32_16x16x32_bf16 v[112:115], v[180:183], v[188:191], v[112:115]
	v_mfma_f32_16x16x32_bf16 v[100:103], v[172:175], v[196:199], v[100:103]
	v_mfma_f32_16x16x32_bf16 v[96:99], v[180:183], v[196:199], v[96:99]
	v_mfma_f32_16x16x32_bf16 v[84:87], v[172:175], v[206:209], v[84:87]
	v_mfma_f32_16x16x32_bf16 v[80:83], v[180:183], v[206:209], v[80:83]
	v_mfma_f32_16x16x32_bf16 v[68:71], v[172:175], v[214:217], v[68:71]
	v_mfma_f32_16x16x32_bf16 v[64:67], v[180:183], v[214:217], v[64:67]
	s_setprio 0
	s_barrier
	s_add_u32 s100, s36, 0x80
	s_addc_u32 s101, s37, 0
	s_add_u32 s58, s36, 0x100080
	s_addc_u32 s59, s37, 0
	s_add_u32 s98, s38, 0x80
	s_addc_u32 s99, s39, 0
	ds_read_b128 v[184:187], v155 offset:49152
	ds_read_b128 v[188:191], v155 offset:50176
	ds_read_b128 v[192:195], v155 offset:51200
	ds_read_b128 v[196:199], v155 offset:52224
	ds_read_b128 v[202:205], v155 offset:53248
	ds_read_b128 v[206:209], v155 offset:54272
	ds_read_b128 v[210:213], v155 offset:55296
	ds_read_b128 v[214:217], v155 offset:56320
	s_add_i32 m0, s31, 0x18000
	s_nop 0
	global_load_lds_dwordx4 v130, s[100:101]
	s_add_i32 m0, s31, 0x1a000
	s_nop 0
	global_load_lds_dwordx4 v134, s[100:101]
	s_add_i32 m0, s31, 0x1c000
	s_nop 0
	global_load_lds_dwordx4 v130, s[58:59]
	s_add_i32 m0, s31, 0x1e000
	s_nop 0
	global_load_lds_dwordx4 v134, s[58:59]
	s_add_i32 m0, s31, 0x8000
	s_nop 0
	global_load_lds_dwordx4 v128, s[98:99]
	s_add_i32 m0, s31, 0xa000
	s_nop 0
	global_load_lds_dwordx4 v132, s[98:99]
	s_waitcnt vmcnt(8)
	s_waitcnt lgkmcnt(0)
	s_barrier
	s_setprio 1
	v_mfma_f32_16x16x32_bf16 v[60:63], v[144:147], v[184:187], v[60:63]
	v_mfma_f32_16x16x32_bf16 v[56:59], v[160:163], v[184:187], v[56:59]
	v_mfma_f32_16x16x32_bf16 v[44:47], v[144:147], v[192:195], v[44:47]
	v_mfma_f32_16x16x32_bf16 v[40:43], v[160:163], v[192:195], v[40:43]
	v_mfma_f32_16x16x32_bf16 v[28:31], v[144:147], v[202:205], v[28:31]
	v_mfma_f32_16x16x32_bf16 v[24:27], v[160:163], v[202:205], v[24:27]
	v_mfma_f32_16x16x32_bf16 v[12:15], v[144:147], v[210:213], v[12:15]
	v_mfma_f32_16x16x32_bf16 v[8:11], v[160:163], v[210:213], v[8:11]
	v_mfma_f32_16x16x32_bf16 v[60:63], v[156:159], v[188:191], v[60:63]
	v_mfma_f32_16x16x32_bf16 v[56:59], v[164:167], v[188:191], v[56:59]
	v_mfma_f32_16x16x32_bf16 v[44:47], v[156:159], v[196:199], v[44:47]
	v_mfma_f32_16x16x32_bf16 v[40:43], v[164:167], v[196:199], v[40:43]
	v_mfma_f32_16x16x32_bf16 v[28:31], v[156:159], v[206:209], v[28:31]
	v_mfma_f32_16x16x32_bf16 v[24:27], v[164:167], v[206:209], v[24:27]
	v_mfma_f32_16x16x32_bf16 v[12:15], v[156:159], v[214:217], v[12:15]
	v_mfma_f32_16x16x32_bf16 v[8:11], v[164:167], v[214:217], v[8:11]
	v_mfma_f32_16x16x32_bf16 v[52:55], v[168:171], v[184:187], v[52:55]
	v_mfma_f32_16x16x32_bf16 v[48:51], v[176:179], v[184:187], v[48:51]
	v_mfma_f32_16x16x32_bf16 v[36:39], v[168:171], v[192:195], v[36:39]
	v_mfma_f32_16x16x32_bf16 v[32:35], v[176:179], v[192:195], v[32:35]
	v_mfma_f32_16x16x32_bf16 v[20:23], v[168:171], v[202:205], v[20:23]
	v_mfma_f32_16x16x32_bf16 v[16:19], v[176:179], v[202:205], v[16:19]
	v_mfma_f32_16x16x32_bf16 v[4:7], v[168:171], v[210:213], v[4:7]
	v_mfma_f32_16x16x32_bf16 v[0:3], v[176:179], v[210:213], v[0:3]
	v_mfma_f32_16x16x32_bf16 v[52:55], v[172:175], v[188:191], v[52:55]
	v_mfma_f32_16x16x32_bf16 v[48:51], v[180:183], v[188:191], v[48:51]
	v_mfma_f32_16x16x32_bf16 v[36:39], v[172:175], v[196:199], v[36:39]
	v_mfma_f32_16x16x32_bf16 v[32:35], v[180:183], v[196:199], v[32:35]
	v_mfma_f32_16x16x32_bf16 v[20:23], v[172:175], v[206:209], v[20:23]
	v_mfma_f32_16x16x32_bf16 v[16:19], v[180:183], v[206:209], v[16:19]
	v_mfma_f32_16x16x32_bf16 v[4:7], v[172:175], v[214:217], v[4:7]
	v_mfma_f32_16x16x32_bf16 v[0:3], v[180:183], v[214:217], v[0:3]
	s_setprio 0
	s_barrier
	s_add_i32 s57, s57, 2
	s_add_u32 s34, s34, 0x100
	s_addc_u32 s35, s35, 0
	s_add_u32 s55, s55, 0x100
	s_addc_u32 s56, s56, 0
	s_cmp_gt_u32 s57, 61
	s_cbranch_scc0 .LBB0_1299
	s_and_b64 vcc, exec, s[6:7]
	s_cbranch_vccz .LBB0_1302
	s_barrier

.LBB0_1409:
	ds_read_b128 v[128:131], v177 offset:0
	ds_read_b128 v[146:149], v177 offset:1024
	ds_read_b128 v[150:153], v177 offset:2048
	ds_read_b128 v[154:157], v177 offset:3072
	ds_read_b128 v[158:161], v178 offset:0
	ds_read_b128 v[162:165], v178 offset:1024
	ds_read_b128 v[166:169], v178 offset:2048
	ds_read_b128 v[170:173], v178 offset:3072
	s_add_i32 s70, s46, 2
	s_add_u32 s44, s42, 0x100
	s_addc_u32 s45, s43, 0
	s_cmp_eq_u32 s37, s46
	s_cselect_b32 s46, s40, s68
	s_cselect_b32 s49, s39, s45
	s_cselect_b32 s48, s38, s44
	s_cselect_b32 s47, s41, s69
	ds_read_b128 v[180:183], v179 offset:0
	ds_read_b128 v[184:187], v179 offset:1024
	ds_read_b128 v[188:191], v179 offset:2048
	ds_read_b128 v[192:195], v179 offset:3072
	ds_read_b128 v[196:199], v179 offset:4096
	ds_read_b128 v[202:205], v179 offset:5120
	ds_read_b128 v[206:209], v179 offset:6144
	ds_read_b128 v[210:213], v179 offset:7168
	s_add_i32 m0, s50, 0xc000
	s_nop 0
	global_load_lds_dwordx4 v140, s[42:43]
	s_add_i32 m0, s50, 0xe000
	s_nop 0
	global_load_lds_dwordx4 v142, s[42:43]
	s_waitcnt vmcnt(8)
	s_waitcnt lgkmcnt(0)
	s_barrier
	s_setprio 1
	v_mfma_f32_16x16x32_bf16 v[124:127], v[128:131], v[180:183], v[124:127]
	v_mfma_f32_16x16x32_bf16 v[120:123], v[150:153], v[180:183], v[120:123]
	v_mfma_f32_16x16x32_bf16 v[108:111], v[128:131], v[188:191], v[108:111]
	v_mfma_f32_16x16x32_bf16 v[104:107], v[150:153], v[188:191], v[104:107]
	v_mfma_f32_16x16x32_bf16 v[92:95], v[128:131], v[196:199], v[92:95]
	v_mfma_f32_16x16x32_bf16 v[88:91], v[150:153], v[196:199], v[88:91]
	v_mfma_f32_16x16x32_bf16 v[76:79], v[128:131], v[206:209], v[76:79]
	v_mfma_f32_16x16x32_bf16 v[72:75], v[150:153], v[206:209], v[72:75]
	v_mfma_f32_16x16x32_bf16 v[124:127], v[146:149], v[184:187], v[124:127]
	v_mfma_f32_16x16x32_bf16 v[120:123], v[154:157], v[184:187], v[120:123]
	v_mfma_f32_16x16x32_bf16 v[108:111], v[146:149], v[192:195], v[108:111]
	v_mfma_f32_16x16x32_bf16 v[104:107], v[154:157], v[192:195], v[104:107]
	v_mfma_f32_16x16x32_bf16 v[92:95], v[146:149], v[202:205], v[92:95]
	v_mfma_f32_16x16x32_bf16 v[88:91], v[154:157], v[202:205], v[88:91]
	v_mfma_f32_16x16x32_bf16 v[76:79], v[146:149], v[210:213], v[76:79]
	v_mfma_f32_16x16x32_bf16 v[72:75], v[154:157], v[210:213], v[72:75]
	v_mfma_f32_16x16x32_bf16 v[116:119], v[158:161], v[180:183], v[116:119]
	v_mfma_f32_16x16x32_bf16 v[112:115], v[166:169], v[180:183], v[112:115]
	v_mfma_f32_16x16x32_bf16 v[100:103], v[158:161], v[188:191], v[100:103]
	v_mfma_f32_16x16x32_bf16 v[96:99], v[166:169], v[188:191], v[96:99]
	v_mfma_f32_16x16x32_bf16 v[84:87], v[158:161], v[196:199], v[84:87]
	v_mfma_f32_16x16x32_bf16 v[80:83], v[166:169], v[196:199], v[80:83]
	v_mfma_f32_16x16x32_bf16 v[68:71], v[158:161], v[206:209], v[68:71]
	v_mfma_f32_16x16x32_bf16 v[64:67], v[166:169], v[206:209], v[64:67]
	v_mfma_f32_16x16x32_bf16 v[116:119], v[162:165], v[184:187], v[116:119]
	v_mfma_f32_16x16x32_bf16 v[112:115], v[170:173], v[184:187], v[112:115]
	v_mfma_f32_16x16x32_bf16 v[100:103], v[162:165], v[192:195], v[100:103]
	v_mfma_f32_16x16x32_bf16 v[96:99], v[170:173], v[192:195], v[96:99]
	v_mfma_f32_16x16x32_bf16 v[84:87], v[162:165], v[202:205], v[84:87]
	v_mfma_f32_16x16x32_bf16 v[80:83], v[170:173], v[202:205], v[80:83]
	v_mfma_f32_16x16x32_bf16 v[68:71], v[162:165], v[210:213], v[68:71]
	v_mfma_f32_16x16x32_bf16 v[64:67], v[170:173], v[210:213], v[64:67]
	s_setprio 0
	s_barrier
	s_add_u32 s42, s46, 0x2b0000
	s_addc_u32 s43, s47, 0
	ds_read_b128 v[180:183], v179 offset:16384
	ds_read_b128 v[184:187], v179 offset:17408
	ds_read_b128 v[188:191], v179 offset:18432
	ds_read_b128 v[192:195], v179 offset:19456
	ds_read_b128 v[196:199], v179 offset:20480
	ds_read_b128 v[202:205], v179 offset:21504
	ds_read_b128 v[206:209], v179 offset:22528
	ds_read_b128 v[210:213], v179 offset:23552
	s_add_i32 m0, s50, 0x10000
	s_nop 0
	global_load_lds_dwordx4 v134, s[46:47]
	s_add_i32 m0, s50, 0x12000
	s_nop 0
	global_load_lds_dwordx4 v138, s[46:47]
	s_add_i32 m0, s50, 0x14000
	s_nop 0
	global_load_lds_dwordx4 v134, s[42:43]
	s_add_i32 m0, s50, 0x16000
	s_nop 0
	global_load_lds_dwordx4 v138, s[42:43]
	s_add_i32 m0, s50, 0x0
	s_nop 0
	global_load_lds_dwordx4 v132, s[48:49]
	s_add_i32 m0, s50, 0x2000
	s_nop 0
	global_load_lds_dwordx4 v136, s[48:49]
	s_waitcnt vmcnt(8)
	s_waitcnt lgkmcnt(0)
	s_barrier
	s_setprio 1
	v_mfma_f32_16x16x32_bf16 v[60:63], v[128:131], v[180:183], v[60:63]
	v_mfma_f32_16x16x32_bf16 v[56:59], v[150:153], v[180:183], v[56:59]
	v_mfma_f32_16x16x32_bf16 v[44:47], v[128:131], v[188:191], v[44:47]
	v_mfma_f32_16x16x32_bf16 v[40:43], v[150:153], v[188:191], v[40:43]
	v_mfma_f32_16x16x32_bf16 v[28:31], v[128:131], v[196:199], v[28:31]
	v_mfma_f32_16x16x32_bf16 v[24:27], v[150:153], v[196:199], v[24:27]
	v_mfma_f32_16x16x32_bf16 v[12:15], v[128:131], v[206:209], v[12:15]
	v_mfma_f32_16x16x32_bf16 v[8:11], v[150:153], v[206:209], v[8:11]
	v_mfma_f32_16x16x32_bf16 v[60:63], v[146:149], v[184:187], v[60:63]
	v_mfma_f32_16x16x32_bf16 v[56:59], v[154:157], v[184:187], v[56:59]
	v_mfma_f32_16x16x32_bf16 v[44:47], v[146:149], v[192:195], v[44:47]
	v_mfma_f32_16x16x32_bf16 v[40:43], v[154:157], v[192:195], v[40:43]
	v_mfma_f32_16x16x32_bf16 v[28:31], v[146:149], v[202:205], v[28:31]
	v_mfma_f32_16x16x32_bf16 v[24:27], v[154:157], v[202:205], v[24:27]
	v_mfma_f32_16x16x32_bf16 v[12:15], v[146:149], v[210:213], v[12:15]
	v_mfma_f32_16x16x32_bf16 v[8:11], v[154:157], v[210:213], v[8:11]
	v_mfma_f32_16x16x32_bf16 v[52:55], v[158:161], v[180:183], v[52:55]
	v_mfma_f32_16x16x32_bf16 v[48:51], v[166:169], v[180:183], v[48:51]
	v_mfma_f32_16x16x32_bf16 v[36:39], v[158:161], v[188:191], v[36:39]
	v_mfma_f32_16x16x32_bf16 v[32:35], v[166:169], v[188:191], v[32:35]
	v_mfma_f32_16x16x32_bf16 v[20:23], v[158:161], v[196:199], v[20:23]
	v_mfma_f32_16x16x32_bf16 v[16:19], v[166:169], v[196:199], v[16:19]
	v_mfma_f32_16x16x32_bf16 v[4:7], v[158:161], v[206:209], v[4:7]
	v_mfma_f32_16x16x32_bf16 v[0:3], v[166:169], v[206:209], v[0:3]
	v_mfma_f32_16x16x32_bf16 v[52:55], v[162:165], v[184:187], v[52:55]
	v_mfma_f32_16x16x32_bf16 v[48:51], v[170:173], v[184:187], v[48:51]
	v_mfma_f32_16x16x32_bf16 v[36:39], v[162:165], v[192:195], v[36:39]
	v_mfma_f32_16x16x32_bf16 v[32:35], v[170:173], v[192:195], v[32:35]
	v_mfma_f32_16x16x32_bf16 v[20:23], v[162:165], v[202:205], v[20:23]
	v_mfma_f32_16x16x32_bf16 v[16:19], v[170:173], v[202:205], v[16:19]
	v_mfma_f32_16x16x32_bf16 v[4:7], v[162:165], v[210:213], v[4:7]
	v_mfma_f32_16x16x32_bf16 v[0:3], v[170:173], v[210:213], v[0:3]
	s_setprio 0
	s_barrier
	s_add_u32 s98, s48, 0x2b0000
	s_addc_u32 s99, s49, 0
	ds_read_b128 v[128:131], v177 offset:32768
	ds_read_b128 v[146:149], v177 offset:33792
	ds_read_b128 v[150:153], v177 offset:34816
	ds_read_b128 v[154:157], v177 offset:35840
	ds_read_b128 v[158:161], v178 offset:32768
	ds_read_b128 v[162:165], v178 offset:33792
	ds_read_b128 v[166:169], v178 offset:34816
	ds_read_b128 v[170:173], v178 offset:35840
	ds_read_b128 v[180:183], v179 offset:32768
	ds_read_b128 v[184:187], v179 offset:33792
	ds_read_b128 v[188:191], v179 offset:34816
	ds_read_b128 v[192:195], v179 offset:35840
	ds_read_b128 v[196:199], v179 offset:36864
	ds_read_b128 v[202:205], v179 offset:37888
	ds_read_b128 v[206:209], v179 offset:38912
	ds_read_b128 v[210:213], v179 offset:39936
	s_add_i32 m0, s50, 0x4000
	s_nop 0
	global_load_lds_dwordx4 v132, s[98:99]
	s_add_i32 m0, s50, 0x6000
	s_nop 0
	global_load_lds_dwordx4 v136, s[98:99]
	s_waitcnt vmcnt(8)
	s_waitcnt lgkmcnt(0)
	s_barrier
	s_setprio 1
	v_mfma_f32_16x16x32_bf16 v[124:127], v[128:131], v[180:183], v[124:127]
	v_mfma_f32_16x16x32_bf16 v[120:123], v[150:153], v[180:183], v[120:123]
	v_mfma_f32_16x16x32_bf16 v[108:111], v[128:131], v[188:191], v[108:111]
	v_mfma_f32_16x16x32_bf16 v[104:107], v[150:153], v[188:191], v[104:107]
	v_mfma_f32_16x16x32_bf16 v[92:95], v[128:131], v[196:199], v[92:95]
	v_mfma_f32_16x16x32_bf16 v[88:91], v[150:153], v[196:199], v[88:91]
	v_mfma_f32_16x16x32_bf16 v[76:79], v[128:131], v[206:209], v[76:79]
	v_mfma_f32_16x16x32_bf16 v[72:75], v[150:153], v[206:209], v[72:75]
	v_mfma_f32_16x16x32_bf16 v[124:127], v[146:149], v[184:187], v[124:127]
	v_mfma_f32_16x16x32_bf16 v[120:123], v[154:157], v[184:187], v[120:123]
	v_mfma_f32_16x16x32_bf16 v[108:111], v[146:149], v[192:195], v[108:111]
	v_mfma_f32_16x16x32_bf16 v[104:107], v[154:157], v[192:195], v[104:107]
	v_mfma_f32_16x16x32_bf16 v[92:95], v[146:149], v[202:205], v[92:95]
	v_mfma_f32_16x16x32_bf16 v[88:91], v[154:157], v[202:205], v[88:91]
	v_mfma_f32_16x16x32_bf16 v[76:79], v[146:149], v[210:213], v[76:79]
	v_mfma_f32_16x16x32_bf16 v[72:75], v[154:157], v[210:213], v[72:75]
	v_mfma_f32_16x16x32_bf16 v[116:119], v[158:161], v[180:183], v[116:119]
	v_mfma_f32_16x16x32_bf16 v[112:115], v[166:169], v[180:183], v[112:115]
	v_mfma_f32_16x16x32_bf16 v[100:103], v[158:161], v[188:191], v[100:103]
	v_mfma_f32_16x16x32_bf16 v[96:99], v[166:169], v[188:191], v[96:99]
	v_mfma_f32_16x16x32_bf16 v[84:87], v[158:161], v[196:199], v[84:87]
	v_mfma_f32_16x16x32_bf16 v[80:83], v[166:169], v[196:199], v[80:83]
	v_mfma_f32_16x16x32_bf16 v[68:71], v[158:161], v[206:209], v[68:71]
	v_mfma_f32_16x16x32_bf16 v[64:67], v[166:169], v[206:209], v[64:67]
	v_mfma_f32_16x16x32_bf16 v[116:119], v[162:165], v[184:187], v[116:119]
	v_mfma_f32_16x16x32_bf16 v[112:115], v[170:173], v[184:187], v[112:115]
	v_mfma_f32_16x16x32_bf16 v[100:103], v[162:165], v[192:195], v[100:103]
	v_mfma_f32_16x16x32_bf16 v[96:99], v[170:173], v[192:195], v[96:99]
	v_mfma_f32_16x16x32_bf16 v[84:87], v[162:165], v[202:205], v[84:87]
	v_mfma_f32_16x16x32_bf16 v[80:83], v[170:173], v[202:205], v[80:83]
	v_mfma_f32_16x16x32_bf16 v[68:71], v[162:165], v[210:213], v[68:71]
	v_mfma_f32_16x16x32_bf16 v[64:67], v[170:173], v[210:213], v[64:67]
	s_setprio 0
	s_barrier
	s_add_u32 s100, s46, 0x80
	s_addc_u32 s101, s47, 0
	s_add_u32 s42, s46, 0x2b0080
	s_addc_u32 s43, s47, 0
	s_add_u32 s98, s48, 0x80
	s_addc_u32 s99, s49, 0
	ds_read_b128 v[180:183], v179 offset:49152
	ds_read_b128 v[184:187], v179 offset:50176
	ds_read_b128 v[188:191], v179 offset:51200
	ds_read_b128 v[192:195], v179 offset:52224
	ds_read_b128 v[196:199], v179 offset:53248
	ds_read_b128 v[202:205], v179 offset:54272
	ds_read_b128 v[206:209], v179 offset:55296
	ds_read_b128 v[210:213], v179 offset:56320
	s_add_i32 m0, s50, 0x18000
	s_nop 0
	global_load_lds_dwordx4 v134, s[100:101]
	s_add_i32 m0, s50, 0x1a000
	s_nop 0
	global_load_lds_dwordx4 v138, s[100:101]
	s_add_i32 m0, s50, 0x1c000
	s_nop 0
	global_load_lds_dwordx4 v134, s[42:43]
	s_add_i32 m0, s50, 0x1e000
	s_nop 0
	global_load_lds_dwordx4 v138, s[42:43]
	s_add_i32 m0, s50, 0x8000
	s_nop 0
	global_load_lds_dwordx4 v132, s[98:99]
	s_add_i32 m0, s50, 0xa000
	s_nop 0
	global_load_lds_dwordx4 v136, s[98:99]
	s_waitcnt vmcnt(8)
	s_waitcnt lgkmcnt(0)
	s_barrier
	s_setprio 1
	v_mfma_f32_16x16x32_bf16 v[60:63], v[128:131], v[180:183], v[60:63]
	v_mfma_f32_16x16x32_bf16 v[56:59], v[150:153], v[180:183], v[56:59]
	v_mfma_f32_16x16x32_bf16 v[44:47], v[128:131], v[188:191], v[44:47]
	v_mfma_f32_16x16x32_bf16 v[40:43], v[150:153], v[188:191], v[40:43]
	v_mfma_f32_16x16x32_bf16 v[28:31], v[128:131], v[196:199], v[28:31]
	v_mfma_f32_16x16x32_bf16 v[24:27], v[150:153], v[196:199], v[24:27]
	v_mfma_f32_16x16x32_bf16 v[12:15], v[128:131], v[206:209], v[12:15]
	v_mfma_f32_16x16x32_bf16 v[8:11], v[150:153], v[206:209], v[8:11]
	v_mfma_f32_16x16x32_bf16 v[60:63], v[146:149], v[184:187], v[60:63]
	v_mfma_f32_16x16x32_bf16 v[56:59], v[154:157], v[184:187], v[56:59]
	v_mfma_f32_16x16x32_bf16 v[44:47], v[146:149], v[192:195], v[44:47]
	v_mfma_f32_16x16x32_bf16 v[40:43], v[154:157], v[192:195], v[40:43]
	v_mfma_f32_16x16x32_bf16 v[28:31], v[146:149], v[202:205], v[28:31]
	v_mfma_f32_16x16x32_bf16 v[24:27], v[154:157], v[202:205], v[24:27]
	v_mfma_f32_16x16x32_bf16 v[12:15], v[146:149], v[210:213], v[12:15]
	v_mfma_f32_16x16x32_bf16 v[8:11], v[154:157], v[210:213], v[8:11]
	v_mfma_f32_16x16x32_bf16 v[52:55], v[158:161], v[180:183], v[52:55]
	v_mfma_f32_16x16x32_bf16 v[48:51], v[166:169], v[180:183], v[48:51]
	v_mfma_f32_16x16x32_bf16 v[36:39], v[158:161], v[188:191], v[36:39]
	v_mfma_f32_16x16x32_bf16 v[32:35], v[166:169], v[188:191], v[32:35]
	v_mfma_f32_16x16x32_bf16 v[20:23], v[158:161], v[196:199], v[20:23]
	v_mfma_f32_16x16x32_bf16 v[16:19], v[166:169], v[196:199], v[16:19]
	v_mfma_f32_16x16x32_bf16 v[4:7], v[158:161], v[206:209], v[4:7]
	v_mfma_f32_16x16x32_bf16 v[0:3], v[166:169], v[206:209], v[0:3]
	v_mfma_f32_16x16x32_bf16 v[52:55], v[162:165], v[184:187], v[52:55]
	v_mfma_f32_16x16x32_bf16 v[48:51], v[170:173], v[184:187], v[48:51]
	v_mfma_f32_16x16x32_bf16 v[36:39], v[162:165], v[192:195], v[36:39]
	v_mfma_f32_16x16x32_bf16 v[32:35], v[170:173], v[192:195], v[32:35]
	v_mfma_f32_16x16x32_bf16 v[20:23], v[162:165], v[202:205], v[20:23]
	v_mfma_f32_16x16x32_bf16 v[16:19], v[170:173], v[202:205], v[16:19]
	v_mfma_f32_16x16x32_bf16 v[4:7], v[162:165], v[210:213], v[4:7]
	v_mfma_f32_16x16x32_bf16 v[0:3], v[170:173], v[210:213], v[0:3]
	s_setprio 0
	s_barrier
	s_add_u32 s68, s68, 0x100
	s_addc_u32 s69, s69, 0
	s_cmp_ge_i32 s70, s67
	s_mov_b64 s[42:43], s[44:45]
	s_mov_b32 s46, s70
	s_cbranch_scc0 .LBB0_1409
	s_and_b64 vcc, exec, s[14:15]
	s_cbranch_vccz .LBB0_1412

	.amdhsa_kernel _Z8mega_fwd4Args
		.amdhsa_group_segment_fixed_size 0
		.amdhsa_private_segment_fixed_size 0
		.amdhsa_kernarg_size 504
		.amdhsa_user_sgpr_count 2
		.amdhsa_user_sgpr_dispatch_ptr 0
		.amdhsa_user_sgpr_queue_ptr 0
		.amdhsa_user_sgpr_kernarg_segment_ptr 1
		.amdhsa_user_sgpr_dispatch_id 0
		.amdhsa_user_sgpr_kernarg_preload_length 0
		.amdhsa_user_sgpr_kernarg_preload_offset 0
		.amdhsa_user_sgpr_private_segment_size 0
		.amdhsa_uses_dynamic_stack 0
		.amdhsa_enable_private_segment 0
		.amdhsa_system_sgpr_workgroup_id_x 1
		.amdhsa_system_sgpr_workgroup_id_y 0
		.amdhsa_system_sgpr_workgroup_id_z 0
		.amdhsa_system_sgpr_workgroup_info 0
		.amdhsa_system_vgpr_workitem_id 0
		.amdhsa_next_free_vgpr 256
		.amdhsa_next_free_sgpr 102
		.amdhsa_accum_offset 256
		.amdhsa_reserve_vcc 1
		.amdhsa_float_round_mode_32 0
		.amdhsa_float_round_mode_16_64 0
		.amdhsa_float_denorm_mode_32 3
		.amdhsa_float_denorm_mode_16_64 3
		.amdhsa_dx10_clamp 1
		.amdhsa_ieee_mode 1
		.amdhsa_fp16_overflow 0
		.amdhsa_tg_split 0
		.amdhsa_exception_fp_ieee_invalid_op 0
		.amdhsa_exception_fp_denorm_src 0
		.amdhsa_exception_fp_ieee_div_zero 0
		.amdhsa_exception_fp_ieee_overflow 0
		.amdhsa_exception_fp_ieee_underflow 0
		.amdhsa_exception_fp_ieee_inexact 0
		.amdhsa_exception_int_div_zero 0
	.end_amdhsa_kernel

amdhsa.kernels:
  - .agpr_count:     0
    .args:
      - .offset:         0
        .size:           248
        .value_kind:     by_value
      - .offset:         248
        .size:           4
        .value_kind:     hidden_block_count_x
      - .offset:         252
        .size:           4
        .value_kind:     hidden_block_count_y
      - .offset:         256
        .size:           4
        .value_kind:     hidden_block_count_z
      - .offset:         260
        .size:           2
        .value_kind:     hidden_group_size_x
      - .offset:         262
        .size:           2
        .value_kind:     hidden_group_size_y
      - .offset:         264
        .size:           2
        .value_kind:     hidden_group_size_z
      - .offset:         266
        .size:           2
        .value_kind:     hidden_remainder_x
      - .offset:         268
        .size:           2
        .value_kind:     hidden_remainder_y
      - .offset:         270
        .size:           2
        .value_kind:     hidden_remainder_z
      - .offset:         288
        .size:           8
        .value_kind:     hidden_global_offset_x
      - .offset:         296
        .size:           8
        .value_kind:     hidden_global_offset_y
      - .offset:         304
        .size:           8
        .value_kind:     hidden_global_offset_z
      - .offset:         312
        .size:           2
        .value_kind:     hidden_grid_dims
      - .offset:         368
        .size:           4
        .value_kind:     hidden_dynamic_lds_size
    .group_segment_fixed_size: 0
    .kernarg_segment_align: 8
    .kernarg_segment_size: 504
    .language:       OpenCL C
    .language_version:
      - 2
      - 0
    .max_flat_workgroup_size: 512
    .name:           _Z8mega_fwd4Args
    .private_segment_fixed_size: 0
    .sgpr_count:     108
    .sgpr_spill_count: 319
    .symbol:         _Z8mega_fwd4Args.kd
    .uniform_work_group_size: 1
    .uses_dynamic_stack: false
    .vgpr_count:     256
    .vgpr_spill_count: 0
    .wavefront_size: 64
